# LN epilogues: residual (x) tile also loaded row-contiguously (4x256 B per instruction) and transposed through LDS into the accumulator layout
# baseline (speedup 1.0000x reference)
.LBB0_94:
	s_mul_hi_u32 s23, s19, 0xaaaaaaab
	s_lshr_b32 s23, s23, 1
	s_mul_i32 s23, s23, 0x24000
	s_waitcnt lgkmcnt(0)
	v_mfma_f32_16x16x32_bf16 v[66:69], v[22:25], v[26:29], v[66:69]
	v_add_u32_e32 v222, s13, v113
	s_mul_hi_u32 s27, s14, 0xaaaaaaab
	s_lshr_b32 s27, s27, 1
	v_mfma_f32_16x16x32_bf16 v[62:65], v[18:21], v[26:29], v[62:65]
	s_mul_i32 s27, s27, 0x24000
	v_subrev_u32_e32 v182, s27, v126
	v_subrev_u32_e32 v191, s27, v127
	v_mfma_f32_16x16x32_bf16 v[58:61], v[10:13], v[26:29], v[58:61]
	v_subrev_u32_e32 v201, s27, v128
	v_mfma_f32_16x16x32_bf16 v[54:57], v[6:9], v[26:29], v[54:57]
	v_subrev_u32_e32 v26, s23, v125
	v_mfma_f32_16x16x32_bf16 v[50:53], v[22:25], v[14:17], v[50:53]
	v_mfma_f32_16x16x32_bf16 v[46:49], v[18:21], v[14:17], v[46:49]
	v_mfma_f32_16x16x32_bf16 v[42:45], v[10:13], v[14:17], v[42:45]
	v_mfma_f32_16x16x32_bf16 v[38:41], v[6:9], v[14:17], v[38:41]
	v_subrev_u32_e32 v14, s23, v129
	v_add_u32_e32 v16, v222, v26
	v_add_u32_e32 v14, v222, v14
	v_mfma_f32_16x16x32_bf16 v[34:37], v[22:25], v[30:33], v[34:37]
	v_subrev_u32_e32 v15, s27, v130
	v_mfma_f32_16x16x32_bf16 v[86:89], v[22:25], v[2:5], v[86:89]
	ds_read_b128 v[22:25], v16
	ds_read_b128 v[174:177], v16 offset:2048
	ds_read_b128 v[178:181], v16 offset:4096
	ds_read_b128 v[202:205], v16 offset:6144
	ds_read_b128 v[206:209], v14 offset:32768
	ds_read_b128 v[210:213], v14 offset:34816
	ds_read_b128 v[214:217], v14 offset:36864
	ds_read_b128 v[218:221], v14 offset:38912
	v_mfma_f32_16x16x32_bf16 v[74:77], v[18:21], v[30:33], v[74:77]
	v_mfma_f32_16x16x32_bf16 v[70:73], v[10:13], v[30:33], v[70:73]
	v_mfma_f32_16x16x32_bf16 v[78:81], v[6:9], v[30:33], v[78:81]
	v_mfma_f32_16x16x32_bf16 v[94:97], v[18:21], v[2:5], v[94:97]
	v_mfma_f32_16x16x32_bf16 v[90:93], v[10:13], v[2:5], v[90:93]
	v_mfma_f32_16x16x32_bf16 v[82:85], v[6:9], v[2:5], v[82:85]
	s_add_i32 s23, s6, 4
	s_mul_i32 s27, s23, 0xab
	s_bfe_u32 s27, s27, 0x70009
	s_mul_i32 s27, s27, 3
	s_sub_i32 s23, s23, s27
	s_and_b32 s23, s23, 0xff
	s_mul_i32 s23, s23, 0xc000
	s_waitcnt vmcnt(6)
	v_add_u32_e32 v2, v222, v15
	v_add_u32_e32 v6, v222, v201
	s_waitcnt lgkmcnt(0)
	v_mfma_f32_16x16x32_bf16 v[66:69], v[206:209], v[174:177], v[66:69]
	s_mov_b64 s[46:47], 0xbdd8180
	s_add_i32 s27, s23, s8
	s_waitcnt lgkmcnt(0)
	v_mfma_f32_16x16x32_bf16 v[62:65], v[210:213], v[174:177], v[62:65]
	s_barrier
	ds_read_b128 v[30:33], v2
	ds_read_b128 v[26:29], v2 offset:2048
	ds_read_b128 v[14:17], v2 offset:4096
	ds_read_b128 v[2:5], v2 offset:6144
	v_mfma_f32_16x16x32_bf16 v[58:61], v[214:217], v[174:177], v[58:61]
	v_add_u32_e32 v7, v222, v191
	s_mov_b32 m0, s27
	s_add_i32 s23, s23, s9
	v_mfma_f32_16x16x32_bf16 v[54:57], v[218:221], v[174:177], v[54:57]
	v_lshl_add_u64 v[174:175], v[108:109], 0, v[98:99]
	v_lshl_add_u64 v[176:177], v[174:175], 0, s[46:47]
	s_mov_b64 s[46:47], 0xbddc180
	v_mfma_f32_16x16x32_bf16 v[34:37], v[206:209], v[22:25], v[34:37]
	s_add_i32 s19, s19, 1
	v_mfma_f32_16x16x32_bf16 v[74:77], v[210:213], v[22:25], v[74:77]
	v_mfma_f32_16x16x32_bf16 v[70:73], v[214:217], v[22:25], v[70:73]
	v_mfma_f32_16x16x32_bf16 v[78:81], v[218:221], v[22:25], v[78:81]
	ds_read_b128 v[22:25], v6
	ds_read_b128 v[18:21], v7
	v_add_u32_e32 v6, v222, v182
	ds_read_b128 v[10:13], v6
	ds_read_b128 v[6:9], v6 offset:2048
	global_load_lds_dwordx4 v[176:177], off
	v_lshl_add_u64 v[176:177], v[174:175], 0, s[46:47]
	s_add_i32 m0, s27, 0x400
	s_mov_b64 s[46:47], 0xbde0180
	global_load_lds_dwordx4 v[176:177], off
	v_lshl_add_u64 v[176:177], v[174:175], 0, s[46:47]
	s_add_i32 m0, s27, 0x800
	s_mov_b64 s[46:47], 0xbde4180
	global_load_lds_dwordx4 v[176:177], off
	v_lshl_add_u64 v[174:175], v[174:175], 0, s[46:47]
	s_add_i32 m0, s27, 0xc00
	s_mov_b64 s[46:47], 0x1b00180
	global_load_lds_dwordx4 v[174:175], off
	v_lshl_add_u64 v[174:175], v[110:111], 0, v[98:99]
	v_lshl_add_u64 v[176:177], v[174:175], 0, s[46:47]
	s_add_i32 m0, s23, 0x8000
	s_mov_b64 s[46:47], 0x1b04180
	global_load_lds_dwordx4 v[176:177], off
	v_lshl_add_u64 v[174:175], v[174:175], 0, s[46:47]
	s_add_i32 m0, s23, 0x8400
	v_mfma_f32_16x16x32_bf16 v[50:53], v[206:209], v[178:181], v[50:53]
	global_load_lds_dwordx4 v[174:175], off
	v_mfma_f32_16x16x32_bf16 v[46:49], v[210:213], v[178:181], v[46:49]
	v_mfma_f32_16x16x32_bf16 v[42:45], v[214:217], v[178:181], v[42:45]
	v_mfma_f32_16x16x32_bf16 v[38:41], v[218:221], v[178:181], v[38:41]
	v_mfma_f32_16x16x32_bf16 v[86:89], v[206:209], v[202:205], v[86:89]
	v_mfma_f32_16x16x32_bf16 v[94:97], v[210:213], v[202:205], v[94:97]
	v_mfma_f32_16x16x32_bf16 v[90:93], v[214:217], v[202:205], v[90:93]
	v_mfma_f32_16x16x32_bf16 v[82:85], v[218:221], v[202:205], v[82:85]
	s_add_i32 s6, s6, 1
	s_add_i32 s13, s13, 0xc000
	s_add_i32 s14, s14, 1
	v_lshl_add_u64 v[108:109], v[108:109], 0, s[2:3]
	s_cmp_eq_u32 s13, 0x9c000
	v_lshl_add_u64 v[110:111], v[110:111], 0, s[2:3]
	s_cbranch_scc0 .LBB0_94
	s_waitcnt lgkmcnt(0)
	v_mfma_f32_16x16x32_bf16 v[34:37], v[22:25], v[30:33], v[34:37]
	v_mfma_f32_16x16x32_bf16 v[74:77], v[18:21], v[30:33], v[74:77]
	v_mfma_f32_16x16x32_bf16 v[70:73], v[10:13], v[30:33], v[70:73]
	v_mfma_f32_16x16x32_bf16 v[30:33], v[6:9], v[30:33], v[78:81]
	v_mfma_f32_16x16x32_bf16 v[66:69], v[22:25], v[26:29], v[66:69]
	v_mfma_f32_16x16x32_bf16 v[62:65], v[18:21], v[26:29], v[62:65]
	v_mfma_f32_16x16x32_bf16 v[58:61], v[10:13], v[26:29], v[58:61]
	v_mfma_f32_16x16x32_bf16 v[26:29], v[6:9], v[26:29], v[54:57]
	v_mfma_f32_16x16x32_bf16 v[50:53], v[22:25], v[14:17], v[50:53]
	v_mfma_f32_16x16x32_bf16 v[46:49], v[18:21], v[14:17], v[46:49]
	v_mfma_f32_16x16x32_bf16 v[42:45], v[10:13], v[14:17], v[42:45]
	v_mfma_f32_16x16x32_bf16 v[14:17], v[6:9], v[14:17], v[38:41]
	v_mfma_f32_16x16x32_bf16 v[22:25], v[22:25], v[2:5], v[86:89]
	s_nop 1
	ds_read_b128 v[38:41], v131
	ds_read_b128 v[54:57], v132 offset:2048
	ds_read_b128 v[78:81], v132 offset:4096
	ds_read_b128 v[86:89], v132 offset:6144
	v_mfma_f32_16x16x32_bf16 v[18:21], v[18:21], v[2:5], v[94:97]
	v_mfma_f32_16x16x32_bf16 v[10:13], v[10:13], v[2:5], v[90:93]
	s_nop 2
	ds_read_b128 v[90:93], v133 offset:32768
	ds_read_b128 v[94:97], v134 offset:34816
	ds_read_b128 v[108:111], v134 offset:36864
	ds_read_b128 v[174:177], v134 offset:38912
	v_mfma_f32_16x16x32_bf16 v[2:5], v[6:9], v[2:5], v[82:85]
	s_waitcnt lgkmcnt(0)
	v_mfma_f32_16x16x32_bf16 v[6:9], v[90:93], v[38:41], v[34:37]
	s_waitcnt vmcnt(6)
	s_waitcnt lgkmcnt(0)
	s_barrier
	v_mfma_f32_16x16x32_bf16 v[34:37], v[94:97], v[38:41], v[74:77]
	v_mfma_f32_16x16x32_bf16 v[70:73], v[108:111], v[38:41], v[70:73]
	v_mfma_f32_16x16x32_bf16 v[30:33], v[174:177], v[38:41], v[30:33]
	v_mfma_f32_16x16x32_bf16 v[38:41], v[90:93], v[54:57], v[66:69]
	v_mfma_f32_16x16x32_bf16 v[62:65], v[94:97], v[54:57], v[62:65]
	v_mfma_f32_16x16x32_bf16 v[58:61], v[108:111], v[54:57], v[58:61]
	v_mfma_f32_16x16x32_bf16 v[26:29], v[174:177], v[54:57], v[26:29]
	v_add_u32_e32 v54, v124, v115
	ds_read_b128 v[54:57], v54
	ds_read_b128 v[66:69], v135 offset:2048
	v_mfma_f32_16x16x32_bf16 v[50:53], v[90:93], v[78:81], v[50:53]
	v_mfma_f32_16x16x32_bf16 v[46:49], v[94:97], v[78:81], v[46:49]
	v_mfma_f32_16x16x32_bf16 v[42:45], v[108:111], v[78:81], v[42:45]
	v_mfma_f32_16x16x32_bf16 v[22:25], v[90:93], v[86:89], v[22:25]
	v_add_u32_e32 v90, 0x20800, v164
	v_mfma_f32_16x16x32_bf16 v[18:21], v[94:97], v[86:89], v[18:21]
	v_add_u32_e32 v94, 0x21000, v164
	v_mfma_f32_16x16x32_bf16 v[10:13], v[108:111], v[86:89], v[10:13]
	v_add_u32_e32 v108, 0x21800, v164
	v_mfma_f32_16x16x32_bf16 v[14:17], v[174:177], v[78:81], v[14:17]
	ds_read_b128 v[74:77], v135 offset:4096
	ds_read_b128 v[78:81], v135 offset:6144
	ds_read_b128 v[82:85], v163
	ds_read_b128 v[90:93], v90
	ds_read_b128 v[94:97], v94
	ds_read_b128 v[108:111], v108
	v_mfma_f32_16x16x32_bf16 v[2:5], v[174:177], v[86:89], v[2:5]
	s_waitcnt lgkmcnt(0)
	v_mfma_f32_16x16x32_bf16 v[6:9], v[82:85], v[54:57], v[6:9]
	v_mfma_f32_16x16x32_bf16 v[34:37], v[90:93], v[54:57], v[34:37]
	v_mfma_f32_16x16x32_bf16 v[70:73], v[94:97], v[54:57], v[70:73]
	v_mfma_f32_16x16x32_bf16 v[30:33], v[108:111], v[54:57], v[30:33]
	v_mfma_f32_16x16x32_bf16 v[54:57], v[90:93], v[66:69], v[62:65]
	s_nop 2
	v_add_u32_e32 v62, v124, v119
	v_mfma_f32_16x16x32_bf16 v[38:41], v[82:85], v[66:69], v[38:41]
	v_mfma_f32_16x16x32_bf16 v[58:61], v[94:97], v[66:69], v[58:61]
	v_mfma_f32_16x16x32_bf16 v[26:29], v[108:111], v[66:69], v[26:29]
	v_mfma_f32_16x16x32_bf16 v[50:53], v[82:85], v[74:77], v[50:53]
	v_mfma_f32_16x16x32_bf16 v[46:49], v[90:93], v[74:77], v[46:49]
	v_mfma_f32_16x16x32_bf16 v[42:45], v[94:97], v[74:77], v[42:45]
	v_mfma_f32_16x16x32_bf16 v[14:17], v[108:111], v[74:77], v[14:17]
	v_mfma_f32_16x16x32_bf16 v[22:25], v[82:85], v[78:81], v[22:25]
	ds_read_b128 v[62:65], v62
	ds_read_b128 v[66:69], v165
	ds_read_b128 v[74:77], v166
	ds_read_b128 v[82:85], v167
	v_mfma_f32_16x16x32_bf16 v[18:21], v[90:93], v[78:81], v[18:21]
	v_mfma_f32_16x16x32_bf16 v[10:13], v[94:97], v[78:81], v[10:13]
	ds_read_b128 v[86:89], v168
	ds_read_b128 v[90:93], v169
	ds_read_b128 v[94:97], v170
	ds_read_b128 v[174:177], v171
	v_mfma_f32_16x16x32_bf16 v[2:5], v[108:111], v[78:81], v[2:5]
	s_waitcnt vmcnt(0)
	s_waitcnt lgkmcnt(0)
	v_mfma_f32_16x16x32_bf16 v[6:9], v[86:89], v[62:65], v[6:9]
	s_waitcnt lgkmcnt(0)
	s_barrier
	v_mfma_f32_16x16x32_bf16 v[34:37], v[90:93], v[62:65], v[34:37]
	v_mfma_f32_16x16x32_bf16 v[70:73], v[94:97], v[62:65], v[70:73]
	v_mfma_f32_16x16x32_bf16 v[30:33], v[174:177], v[62:65], v[30:33]
	v_mfma_f32_16x16x32_bf16 v[38:41], v[86:89], v[66:69], v[38:41]
	v_mfma_f32_16x16x32_bf16 v[54:57], v[90:93], v[66:69], v[54:57]
	v_mfma_f32_16x16x32_bf16 v[58:61], v[94:97], v[66:69], v[58:61]
	v_mfma_f32_16x16x32_bf16 v[26:29], v[174:177], v[66:69], v[26:29]
	v_mfma_f32_16x16x32_bf16 v[50:53], v[86:89], v[74:77], v[50:53]
	v_mfma_f32_16x16x32_bf16 v[46:49], v[90:93], v[74:77], v[46:49]
	v_mfma_f32_16x16x32_bf16 v[42:45], v[94:97], v[74:77], v[42:45]
	v_mfma_f32_16x16x32_bf16 v[14:17], v[174:177], v[74:77], v[14:17]
	ds_read_b128 v[62:65], v164 offset:38912
	ds_read_b128 v[66:69], v164 offset:36864
	ds_read_b128 v[74:77], v164 offset:34816
	ds_read_b128 v[78:81], v161 offset:32768
	v_mfma_f32_16x16x32_bf16 v[22:25], v[86:89], v[82:85], v[22:25]
	v_mfma_f32_16x16x32_bf16 v[18:21], v[90:93], v[82:85], v[18:21]
	v_mfma_f32_16x16x32_bf16 v[10:13], v[94:97], v[82:85], v[10:13]
	ds_read_b128 v[86:89], v173 offset:6144
	ds_read_b128 v[90:93], v173 offset:4096
	ds_read_b128 v[94:97], v173 offset:2048
	ds_read_b128 v[108:111], v172
	v_mfma_f32_16x16x32_bf16 v[2:5], v[174:177], v[82:85], v[2:5]
	s_waitcnt lgkmcnt(0)
	v_mfma_f32_16x16x32_bf16 v[38:41], v[78:81], v[94:97], v[38:41]
	v_add_u32_e32 v82, v114, v119
	v_add_u32_e32 v172, v118, v119
	v_mfma_f32_16x16x32_bf16 v[54:57], v[74:77], v[94:97], v[54:57]
	v_mfma_f32_16x16x32_bf16 v[58:61], v[66:69], v[94:97], v[58:61]
	v_mfma_f32_16x16x32_bf16 v[26:29], v[62:65], v[94:97], v[26:29]
	v_add_u32_e32 v94, v117, v119
	v_mfma_f32_16x16x32_bf16 v[50:53], v[78:81], v[90:93], v[50:53]
	v_mfma_f32_16x16x32_bf16 v[46:49], v[74:77], v[90:93], v[46:49]
	v_mfma_f32_16x16x32_bf16 v[42:45], v[66:69], v[90:93], v[42:45]
	v_mfma_f32_16x16x32_bf16 v[14:17], v[62:65], v[90:93], v[14:17]
	v_add_u32_e32 v90, v116, v119
	v_mfma_f32_16x16x32_bf16 v[6:9], v[78:81], v[108:111], v[6:9]
	v_mfma_f32_16x16x32_bf16 v[34:37], v[74:77], v[108:111], v[34:37]
	v_mfma_f32_16x16x32_bf16 v[70:73], v[66:69], v[108:111], v[70:73]
	v_mfma_f32_16x16x32_bf16 v[30:33], v[62:65], v[108:111], v[30:33]
	v_mfma_f32_16x16x32_bf16 v[78:81], v[78:81], v[86:89], v[22:25]
	s_nop 2
	ds_read_b128 v[22:25], v82
	ds_read_b128 v[82:85], v90 offset:2048
	v_mfma_f32_16x16x32_bf16 v[74:77], v[74:77], v[86:89], v[18:21]
	s_nop 2
	ds_read_b128 v[18:21], v90 offset:4096
	ds_read_b128 v[90:93], v90 offset:6144
	v_mfma_f32_16x16x32_bf16 v[66:69], v[66:69], v[86:89], v[10:13]
	s_nop 2
	ds_read_b128 v[10:13], v94 offset:32768
	ds_read_b128 v[94:97], v172 offset:34816
	ds_read_b128 v[108:111], v172 offset:36864
	ds_read_b128 v[172:175], v172 offset:38912
	v_mfma_f32_16x16x32_bf16 v[2:5], v[62:65], v[86:89], v[2:5]
	s_waitcnt vmcnt(0)
	s_waitcnt lgkmcnt(0)
	v_mfma_f32_16x16x32_bf16 v[2:5], v[172:175], v[90:93], v[2:5]
	s_waitcnt lgkmcnt(0)
	s_barrier
	v_mfma_f32_16x16x32_bf16 v[62:65], v[10:13], v[22:25], v[6:9]
	v_mfma_f32_16x16x32_bf16 v[86:89], v[94:97], v[22:25], v[34:37]
	v_mfma_f32_16x16x32_bf16 v[70:73], v[108:111], v[22:25], v[70:73]
	v_mfma_f32_16x16x32_bf16 v[176:179], v[172:175], v[22:25], v[30:33]
	v_mfma_f32_16x16x32_bf16 v[202:205], v[10:13], v[82:85], v[38:41]
	v_mfma_f32_16x16x32_bf16 v[54:57], v[94:97], v[82:85], v[54:57]
	v_mfma_f32_16x16x32_bf16 v[58:61], v[108:111], v[82:85], v[58:61]
	v_mfma_f32_16x16x32_bf16 v[34:37], v[172:175], v[82:85], v[26:29]
	v_mfma_f32_16x16x32_bf16 v[30:33], v[10:13], v[18:21], v[50:53]
	v_mfma_f32_16x16x32_bf16 v[26:29], v[94:97], v[18:21], v[46:49]
	v_mfma_f32_16x16x32_bf16 v[22:25], v[108:111], v[18:21], v[42:45]
	v_mfma_f32_16x16x32_bf16 v[18:21], v[172:175], v[18:21], v[14:17]
	v_mfma_f32_16x16x32_bf16 v[14:17], v[10:13], v[90:93], v[78:81]
	v_mfma_f32_16x16x32_bf16 v[10:13], v[94:97], v[90:93], v[74:77]
	v_mfma_f32_16x16x32_bf16 v[6:9], v[108:111], v[90:93], v[66:69]
	s_mul_hi_i32 s64, s60, 0x2aaaaaab
	s_lshr_b32 s65, s64, 31
	s_ashr_i32 s64, s64, 2
	s_add_i32 s6, s64, s65
	s_mul_i32 s64, s6, 24
	s_sub_i32 s13, s60, s64
	v_readfirstlane_b32 s64, v137
	s_lshr_b32 s64, s64, 6
	s_and_b32 s14, s64, 1
	s_lshr_b32 s64, s64, 1
	s_lshl_b32 s64, s64, 6
	s_lshl_b32 s36, s13, 8
	s_add_i32 s36, s36, s64
	s_lshl_b32 s37, s6, 7
	s_lshl_b32 s64, s14, 6
	s_add_i32 s37, s37, s64
	s_add_i32 s64, s36, 0xfffff000
	s_ashr_i32 s64, s64, 10
	s_add_i32 s64, s64, 1
	s_cmpk_lt_i32 s36, 0x1000
	s_cselect_b32 s52, 0, s64
	v_readlane_b32 s53, v255, 40
	v_and_b32_e32 v250, 63, v137
	v_and_b32_e32 v251, 15, v250
	v_lshrrev_b32_e32 v252, 4, v250
	s_mul_i32 s64, s53, 3
	s_add_i32 s64, s64, s52
	s_mul_i32 s64, s64, 0x6000
	s_add_u32 s22, s94, 0x6300000
	s_addc_u32 s23, s95, 0
	s_add_u32 s22, s22, s64
	s_addc_u32 s23, s23, 0
	s_add_u32 s26, s94, 0x6348000
	s_addc_u32 s27, s95, 0
	v_add_u32_e32 v242, s36, v251
	v_lshlrev_b32_e32 v242, 12, v242
	s_lshl_b32 s64, s37, 2
	v_lshl_add_u32 v242, v252, 4, v242
	v_add_u32_e32 v242, s64, v242
	s_add_i32 s65, s37, 2048
	s_lshl_b32 s65, s65, 2
	v_lshl_add_u32 v246, v252, 4, s65
	v_readfirstlane_b32 s64, v137
	s_lshr_b32 s64, s64, 6
	s_lshl_b32 s64, s64, 14
	v_and_b32_e32 v242, 3, v251
	v_xor_b32_e32 v242, v242, v252
	v_lshlrev_b32_e32 v242, 4, v242
	v_lshl_add_u32 v242, v251, 8, v242
	v_add_u32_e32 v242, s64, v242
	v_lshl_add_u32 v243, v250, 4, s64
	v_add_u32_e32 v244, s36, v252
	v_lshlrev_b32_e32 v244, 12, v244
	v_xor_b32_e32 v245, v251, v252
	v_lshl_add_u32 v244, v245, 4, v244
	s_lshl_b32 s64, s37, 2
	v_add_u32_e32 v244, s64, v244
	global_load_dwordx4 v[226:229], v246, s[22:23]
	global_load_dwordx4 v[230:233], v246, s[22:23] offset:64
	global_load_dwordx4 v[234:237], v246, s[22:23] offset:128
	global_load_dwordx4 v[238:241], v246, s[22:23] offset:192
	global_load_dwordx4 v[38:41], v244, s[26:27]
	v_add_u32_e32 v245, 0x4000, v244
	global_load_dwordx4 v[42:45], v245, s[26:27]
	v_add_u32_e32 v245, 0x8000, v244
	global_load_dwordx4 v[46:49], v245, s[26:27]
	v_add_u32_e32 v245, 0xc000, v244
	global_load_dwordx4 v[50:53], v245, s[26:27]
	v_add_u32_e32 v245, 0x10000, v244
	global_load_dwordx4 v[66:69], v245, s[26:27]
	v_add_u32_e32 v245, 0x14000, v244
	global_load_dwordx4 v[74:77], v245, s[26:27]
	v_add_u32_e32 v245, 0x18000, v244
	global_load_dwordx4 v[78:81], v245, s[26:27]
	v_add_u32_e32 v245, 0x1c000, v244
	global_load_dwordx4 v[82:85], v245, s[26:27]
	v_add_u32_e32 v245, 0x20000, v244
	global_load_dwordx4 v[90:93], v245, s[26:27]
	v_add_u32_e32 v245, 0x24000, v244
	global_load_dwordx4 v[94:97], v245, s[26:27]
	v_add_u32_e32 v245, 0x28000, v244
	global_load_dwordx4 v[108:111], v245, s[26:27]
	v_add_u32_e32 v245, 0x2c000, v244
	global_load_dwordx4 v[172:175], v245, s[26:27]
	v_add_u32_e32 v245, 0x30000, v244
	global_load_dwordx4 v[206:209], v245, s[26:27]
	v_add_u32_e32 v245, 0x34000, v244
	global_load_dwordx4 v[210:213], v245, s[26:27]
	v_add_u32_e32 v245, 0x38000, v244
	global_load_dwordx4 v[214:217], v245, s[26:27]
	v_add_u32_e32 v245, 0x3c000, v244
	global_load_dwordx4 v[218:221], v245, s[26:27]
	s_waitcnt vmcnt(15)
	ds_write_b128 v243, v[38:41] offset:0
	s_waitcnt vmcnt(14)
	ds_write_b128 v243, v[42:45] offset:1024
	s_waitcnt vmcnt(13)
	ds_write_b128 v243, v[46:49] offset:2048
	s_waitcnt vmcnt(12)
	ds_write_b128 v243, v[50:53] offset:3072
	s_waitcnt vmcnt(11)
	ds_write_b128 v243, v[66:69] offset:4096
	s_waitcnt vmcnt(10)
	ds_write_b128 v243, v[74:77] offset:5120
	s_waitcnt vmcnt(9)
	ds_write_b128 v243, v[78:81] offset:6144
	s_waitcnt vmcnt(8)
	ds_write_b128 v243, v[82:85] offset:7168
	s_waitcnt vmcnt(7)
	ds_write_b128 v243, v[90:93] offset:8192
	s_waitcnt vmcnt(6)
	ds_write_b128 v243, v[94:97] offset:9216
	s_waitcnt vmcnt(5)
	ds_write_b128 v243, v[108:111] offset:10240
	s_waitcnt vmcnt(4)
	ds_write_b128 v243, v[172:175] offset:11264
	s_waitcnt vmcnt(3)
	ds_write_b128 v243, v[206:209] offset:12288
	s_waitcnt vmcnt(2)
	ds_write_b128 v243, v[210:213] offset:13312
	s_waitcnt vmcnt(1)
	ds_write_b128 v243, v[214:217] offset:14336
	s_waitcnt vmcnt(0)
	ds_write_b128 v243, v[218:221] offset:15360
	s_waitcnt lgkmcnt(0)
	ds_read_b128 v[38:41], v242 offset:0
	ds_read_b128 v[42:45], v242 offset:64
	ds_read_b128 v[46:49], v242 offset:128
	ds_read_b128 v[50:53], v242 offset:192
	ds_read_b128 v[66:69], v242 offset:4096
	ds_read_b128 v[74:77], v242 offset:4160
	ds_read_b128 v[78:81], v242 offset:4224
	ds_read_b128 v[82:85], v242 offset:4288
	ds_read_b128 v[90:93], v242 offset:8192
	ds_read_b128 v[94:97], v242 offset:8256
	ds_read_b128 v[108:111], v242 offset:8320
	ds_read_b128 v[172:175], v242 offset:8384
	ds_read_b128 v[206:209], v242 offset:12288
	ds_read_b128 v[210:213], v242 offset:12352
	ds_read_b128 v[214:217], v242 offset:12416
	ds_read_b128 v[218:221], v242 offset:12480
	v_mov_b32_e32 v248, 0x3fd744fd
	v_mov_b32_e32 v249, 0x3fd744fd
	s_waitcnt lgkmcnt(12)
	v_pk_mul_f32 v[38:39], v[38:39], v[248:249]
	v_pk_mul_f32 v[40:41], v[40:41], v[248:249]
	v_pk_fma_f32 v[62:63], v[62:63], v[226:227], v[38:39]
	v_pk_fma_f32 v[64:65], v[64:65], v[228:229], v[40:41]
	v_pk_mul_f32 v[42:43], v[42:43], v[248:249]
	v_pk_mul_f32 v[44:45], v[44:45], v[248:249]
	v_pk_fma_f32 v[86:87], v[86:87], v[230:231], v[42:43]
	v_pk_fma_f32 v[88:89], v[88:89], v[232:233], v[44:45]
	v_pk_mul_f32 v[46:47], v[46:47], v[248:249]
	v_pk_mul_f32 v[48:49], v[48:49], v[248:249]
	v_pk_fma_f32 v[70:71], v[70:71], v[234:235], v[46:47]
	v_pk_fma_f32 v[72:73], v[72:73], v[236:237], v[48:49]
	v_pk_mul_f32 v[50:51], v[50:51], v[248:249]
	v_pk_mul_f32 v[52:53], v[52:53], v[248:249]
	v_pk_fma_f32 v[176:177], v[176:177], v[238:239], v[50:51]
	v_pk_fma_f32 v[178:179], v[178:179], v[240:241], v[52:53]
	s_waitcnt lgkmcnt(8)
	v_pk_mul_f32 v[66:67], v[66:67], v[248:249]
	v_pk_mul_f32 v[68:69], v[68:69], v[248:249]
	v_pk_fma_f32 v[202:203], v[202:203], v[226:227], v[66:67]
	v_pk_fma_f32 v[204:205], v[204:205], v[228:229], v[68:69]
	v_pk_mul_f32 v[74:75], v[74:75], v[248:249]
	v_pk_mul_f32 v[76:77], v[76:77], v[248:249]
	v_pk_fma_f32 v[54:55], v[54:55], v[230:231], v[74:75]
	v_pk_fma_f32 v[56:57], v[56:57], v[232:233], v[76:77]
	v_pk_mul_f32 v[78:79], v[78:79], v[248:249]
	v_pk_mul_f32 v[80:81], v[80:81], v[248:249]
	v_pk_fma_f32 v[58:59], v[58:59], v[234:235], v[78:79]
	v_pk_fma_f32 v[60:61], v[60:61], v[236:237], v[80:81]
	v_pk_mul_f32 v[82:83], v[82:83], v[248:249]
	v_pk_mul_f32 v[84:85], v[84:85], v[248:249]
	v_pk_fma_f32 v[34:35], v[34:35], v[238:239], v[82:83]
	v_pk_fma_f32 v[36:37], v[36:37], v[240:241], v[84:85]
	s_waitcnt lgkmcnt(4)
	v_pk_mul_f32 v[90:91], v[90:91], v[248:249]
	v_pk_mul_f32 v[92:93], v[92:93], v[248:249]
	v_pk_fma_f32 v[30:31], v[30:31], v[226:227], v[90:91]
	v_pk_fma_f32 v[32:33], v[32:33], v[228:229], v[92:93]
	v_pk_mul_f32 v[94:95], v[94:95], v[248:249]
	v_pk_mul_f32 v[96:97], v[96:97], v[248:249]
	v_pk_fma_f32 v[26:27], v[26:27], v[230:231], v[94:95]
	v_pk_fma_f32 v[28:29], v[28:29], v[232:233], v[96:97]
	v_pk_mul_f32 v[108:109], v[108:109], v[248:249]
	v_pk_mul_f32 v[110:111], v[110:111], v[248:249]
	v_pk_fma_f32 v[22:23], v[22:23], v[234:235], v[108:109]
	v_pk_fma_f32 v[24:25], v[24:25], v[236:237], v[110:111]
	v_pk_mul_f32 v[172:173], v[172:173], v[248:249]
	v_pk_mul_f32 v[174:175], v[174:175], v[248:249]
	v_pk_fma_f32 v[18:19], v[18:19], v[238:239], v[172:173]
	v_pk_fma_f32 v[20:21], v[20:21], v[240:241], v[174:175]
	s_waitcnt lgkmcnt(0)
	v_pk_mul_f32 v[206:207], v[206:207], v[248:249]
	v_pk_mul_f32 v[208:209], v[208:209], v[248:249]
	v_pk_fma_f32 v[14:15], v[14:15], v[226:227], v[206:207]
	v_pk_fma_f32 v[16:17], v[16:17], v[228:229], v[208:209]
	v_pk_mul_f32 v[210:211], v[210:211], v[248:249]
	v_pk_mul_f32 v[212:213], v[212:213], v[248:249]
	v_pk_fma_f32 v[10:11], v[10:11], v[230:231], v[210:211]
	v_pk_fma_f32 v[12:13], v[12:13], v[232:233], v[212:213]
	v_pk_mul_f32 v[214:215], v[214:215], v[248:249]
	v_pk_mul_f32 v[216:217], v[216:217], v[248:249]
	v_pk_fma_f32 v[6:7], v[6:7], v[234:235], v[214:215]
	v_pk_fma_f32 v[8:9], v[8:9], v[236:237], v[216:217]
	v_pk_mul_f32 v[218:219], v[218:219], v[248:249]
	v_pk_mul_f32 v[220:221], v[220:221], v[248:249]
	v_pk_fma_f32 v[2:3], v[2:3], v[238:239], v[218:219]
	v_pk_fma_f32 v[4:5], v[4:5], v[240:241], v[220:221]
	v_pk_mul_f32 v[208:209], v[62:63], v[62:63]
	v_pk_add_f32 v[206:207], v[62:63], v[64:65]
	v_pk_fma_f32 v[208:209], v[64:65], v[64:65], v[208:209]
	v_pk_add_f32 v[206:207], v[206:207], v[86:87]
	v_pk_fma_f32 v[208:209], v[86:87], v[86:87], v[208:209]
	v_pk_add_f32 v[206:207], v[206:207], v[88:89]
	v_pk_fma_f32 v[208:209], v[88:89], v[88:89], v[208:209]
	v_pk_add_f32 v[206:207], v[206:207], v[70:71]
	v_pk_fma_f32 v[208:209], v[70:71], v[70:71], v[208:209]
	v_pk_add_f32 v[206:207], v[206:207], v[72:73]
	v_pk_fma_f32 v[208:209], v[72:73], v[72:73], v[208:209]
	v_pk_add_f32 v[206:207], v[206:207], v[176:177]
	v_pk_fma_f32 v[208:209], v[176:177], v[176:177], v[208:209]
	v_pk_add_f32 v[206:207], v[206:207], v[178:179]
	v_pk_fma_f32 v[208:209], v[178:179], v[178:179], v[208:209]
	v_add_f32_e32 v206, v206, v207
	v_add_f32_e32 v208, v208, v209
	v_pk_mul_f32 v[212:213], v[202:203], v[202:203]
	v_pk_add_f32 v[210:211], v[202:203], v[204:205]
	v_pk_fma_f32 v[212:213], v[204:205], v[204:205], v[212:213]
	v_pk_add_f32 v[210:211], v[210:211], v[54:55]
	v_pk_fma_f32 v[212:213], v[54:55], v[54:55], v[212:213]
	v_pk_add_f32 v[210:211], v[210:211], v[56:57]
	v_pk_fma_f32 v[212:213], v[56:57], v[56:57], v[212:213]
	v_pk_add_f32 v[210:211], v[210:211], v[58:59]
	v_pk_fma_f32 v[212:213], v[58:59], v[58:59], v[212:213]
	v_pk_add_f32 v[210:211], v[210:211], v[60:61]
	v_pk_fma_f32 v[212:213], v[60:61], v[60:61], v[212:213]
	v_pk_add_f32 v[210:211], v[210:211], v[34:35]
	v_pk_fma_f32 v[212:213], v[34:35], v[34:35], v[212:213]
	v_pk_add_f32 v[210:211], v[210:211], v[36:37]
	v_pk_fma_f32 v[212:213], v[36:37], v[36:37], v[212:213]
	v_add_f32_e32 v210, v210, v211
	v_add_f32_e32 v212, v212, v213
	v_pk_mul_f32 v[216:217], v[30:31], v[30:31]
	v_pk_add_f32 v[214:215], v[30:31], v[32:33]
	v_pk_fma_f32 v[216:217], v[32:33], v[32:33], v[216:217]
	v_pk_add_f32 v[214:215], v[214:215], v[26:27]
	v_pk_fma_f32 v[216:217], v[26:27], v[26:27], v[216:217]
	v_pk_add_f32 v[214:215], v[214:215], v[28:29]
	v_pk_fma_f32 v[216:217], v[28:29], v[28:29], v[216:217]
	v_pk_add_f32 v[214:215], v[214:215], v[22:23]
	v_pk_fma_f32 v[216:217], v[22:23], v[22:23], v[216:217]
	v_pk_add_f32 v[214:215], v[214:215], v[24:25]
	v_pk_fma_f32 v[216:217], v[24:25], v[24:25], v[216:217]
	v_pk_add_f32 v[214:215], v[214:215], v[18:19]
	v_pk_fma_f32 v[216:217], v[18:19], v[18:19], v[216:217]
	v_pk_add_f32 v[214:215], v[214:215], v[20:21]
	v_pk_fma_f32 v[216:217], v[20:21], v[20:21], v[216:217]
	v_add_f32_e32 v214, v214, v215
	v_add_f32_e32 v216, v216, v217
	v_pk_mul_f32 v[220:221], v[14:15], v[14:15]
	v_pk_add_f32 v[218:219], v[14:15], v[16:17]
	v_pk_fma_f32 v[220:221], v[16:17], v[16:17], v[220:221]
	v_pk_add_f32 v[218:219], v[218:219], v[10:11]
	v_pk_fma_f32 v[220:221], v[10:11], v[10:11], v[220:221]
	v_pk_add_f32 v[218:219], v[218:219], v[12:13]
	v_pk_fma_f32 v[220:221], v[12:13], v[12:13], v[220:221]
	v_pk_add_f32 v[218:219], v[218:219], v[6:7]
	v_pk_fma_f32 v[220:221], v[6:7], v[6:7], v[220:221]
	v_pk_add_f32 v[218:219], v[218:219], v[8:9]
	v_pk_fma_f32 v[220:221], v[8:9], v[8:9], v[220:221]
	v_pk_add_f32 v[218:219], v[218:219], v[2:3]
	v_pk_fma_f32 v[220:221], v[2:3], v[2:3], v[220:221]
	v_pk_add_f32 v[218:219], v[218:219], v[4:5]
	v_pk_fma_f32 v[220:221], v[4:5], v[4:5], v[220:221]
	v_add_f32_e32 v218, v218, v219
	v_add_f32_e32 v220, v220, v221
	s_nop 1
	v_permlane16_swap_b32_e32 v206, v210
	v_permlane16_swap_b32_e32 v214, v218
	v_permlane16_swap_b32_e32 v208, v212
	v_permlane16_swap_b32_e32 v216, v220
	v_add_f32_e32 v206, v206, v210
	v_add_f32_e32 v214, v214, v218
	v_add_f32_e32 v208, v208, v212
	v_add_f32_e32 v216, v216, v220
	s_nop 1
	v_permlane32_swap_b32_e32 v206, v214
	v_permlane32_swap_b32_e32 v208, v216
	v_add_f32_e32 v248, v206, v214
	v_add_f32_e32 v249, v208, v216
	s_lshl_b32 s64, s53, 1
	s_add_i32 s64, s64, 0x2c7e91a0
	v_mov_b32_e32 v218, v248
	v_mov_b32_e32 v219, s64
	v_mov_b32_e32 v220, v249
	v_mov_b32_e32 v221, s64
	v_mov_b32_e32 v249, s64
	s_add_u32 s44, s94, 0xc9d8000
	s_addc_u32 s45, s95, 0
	v_add_u32_e32 v247, s36, v250
	v_lshlrev_b32_e32 v247, 4, v247
	s_lshl_b32 s65, s6, 1
	s_add_i32 s65, s65, s14
	s_mul_i32 s65, s65, 0x18000
	v_add_u32_e32 v246, s65, v247
	global_store_dwordx4 v246, v[218:221], s[44:45] sc1
	v_readlane_b32 s46, v253, 11
	v_readlane_b32 s47, v253, 12
	v_readlane_b32 s48, v253, 13
	v_readlane_b32 s49, v253, 14
	s_lshl_b32 s64, s53, 10
	s_add_i32 s64, s64, s37
	s_lshl_b32 s64, s64, 2
	v_lshl_add_u32 v222, v252, 4, s64
	s_nop 3
	global_load_dwordx4 v[66:69], v222, s[46:47]
	global_load_dwordx4 v[74:77], v222, s[46:47] offset:64
	global_load_dwordx4 v[78:81], v222, s[46:47] offset:128
	global_load_dwordx4 v[82:85], v222, s[46:47] offset:192
	global_load_dwordx4 v[90:93], v222, s[48:49]
	global_load_dwordx4 v[94:97], v222, s[48:49] offset:64
	global_load_dwordx4 v[108:111], v222, s[48:49] offset:128
	global_load_dwordx4 v[172:175], v222, s[48:49] offset:192
	s_add_i32 s64, s37, 3072
	s_lshl_b32 s64, s64, 2
	v_lshl_add_u32 v222, v252, 4, s64
	v_add_u32_e32 v246, 0x1000, v222
	global_load_dwordx4 v[38:41], v222, s[22:23]
	global_load_dwordx4 v[42:45], v222, s[22:23] offset:64
	global_load_dwordx4 v[46:49], v222, s[22:23] offset:128
	global_load_dwordx4 v[50:53], v222, s[22:23] offset:192
	s_mov_b32 s65, 0x40000

.LBB0_413:
	s_mul_hi_u32 s27, s23, 0xaaaaaaab
	s_lshr_b32 s27, s27, 1
	s_mul_i32 s27, s27, 0x24000
	s_waitcnt lgkmcnt(0)
	v_mfma_f32_16x16x32_bf16 v[66:69], v[22:25], v[26:29], v[66:69]
	v_add_u32_e32 v222, s14, v113
	s_mul_hi_u32 s34, s19, 0xaaaaaaab
	s_lshr_b32 s34, s34, 1
	v_mfma_f32_16x16x32_bf16 v[62:65], v[18:21], v[26:29], v[62:65]
	s_mul_i32 s34, s34, 0x24000
	v_subrev_u32_e32 v182, s34, v126
	v_subrev_u32_e32 v191, s34, v127
	v_mfma_f32_16x16x32_bf16 v[58:61], v[10:13], v[26:29], v[58:61]
	v_subrev_u32_e32 v201, s34, v128
	v_mfma_f32_16x16x32_bf16 v[54:57], v[6:9], v[26:29], v[54:57]
	v_subrev_u32_e32 v26, s27, v125
	v_mfma_f32_16x16x32_bf16 v[50:53], v[22:25], v[14:17], v[50:53]
	v_mfma_f32_16x16x32_bf16 v[46:49], v[18:21], v[14:17], v[46:49]
	v_mfma_f32_16x16x32_bf16 v[42:45], v[10:13], v[14:17], v[42:45]
	v_mfma_f32_16x16x32_bf16 v[38:41], v[6:9], v[14:17], v[38:41]
	v_subrev_u32_e32 v14, s27, v129
	v_add_u32_e32 v16, v222, v26
	v_add_u32_e32 v14, v222, v14
	v_mfma_f32_16x16x32_bf16 v[34:37], v[22:25], v[30:33], v[34:37]
	v_subrev_u32_e32 v15, s34, v130
	v_mfma_f32_16x16x32_bf16 v[86:89], v[22:25], v[2:5], v[86:89]
	ds_read_b128 v[22:25], v16
	ds_read_b128 v[174:177], v16 offset:2048
	ds_read_b128 v[178:181], v16 offset:4096
	ds_read_b128 v[202:205], v16 offset:6144
	ds_read_b128 v[206:209], v14 offset:32768
	ds_read_b128 v[210:213], v14 offset:34816
	ds_read_b128 v[214:217], v14 offset:36864
	ds_read_b128 v[218:221], v14 offset:38912
	v_mfma_f32_16x16x32_bf16 v[74:77], v[18:21], v[30:33], v[74:77]
	v_mfma_f32_16x16x32_bf16 v[70:73], v[10:13], v[30:33], v[70:73]
	v_mfma_f32_16x16x32_bf16 v[78:81], v[6:9], v[30:33], v[78:81]
	v_mfma_f32_16x16x32_bf16 v[94:97], v[18:21], v[2:5], v[94:97]
	v_mfma_f32_16x16x32_bf16 v[90:93], v[10:13], v[2:5], v[90:93]
	v_mfma_f32_16x16x32_bf16 v[82:85], v[6:9], v[2:5], v[82:85]
	s_add_i32 s27, s13, 4
	s_mul_i32 s34, s27, 0xab
	s_bfe_u32 s34, s34, 0x70009
	s_mul_i32 s34, s34, 3
	s_sub_i32 s27, s27, s34
	s_and_b32 s27, s27, 0xff
	s_mul_i32 s27, s27, 0xc000
	s_waitcnt vmcnt(6)
	v_add_u32_e32 v2, v222, v15
	v_add_u32_e32 v6, v222, v201
	s_waitcnt lgkmcnt(0)
	v_mfma_f32_16x16x32_bf16 v[66:69], v[206:209], v[174:177], v[66:69]
	s_mov_b64 s[36:37], 0xe1d8180
	s_add_i32 s34, s27, s8
	s_waitcnt lgkmcnt(0)
	v_mfma_f32_16x16x32_bf16 v[62:65], v[210:213], v[174:177], v[62:65]
	s_barrier
	ds_read_b128 v[30:33], v2
	ds_read_b128 v[26:29], v2 offset:2048
	ds_read_b128 v[14:17], v2 offset:4096
	ds_read_b128 v[2:5], v2 offset:6144
	v_mfma_f32_16x16x32_bf16 v[58:61], v[214:217], v[174:177], v[58:61]
	v_add_u32_e32 v7, v222, v191
	s_mov_b32 m0, s34
	s_add_i32 s27, s27, s9
	v_mfma_f32_16x16x32_bf16 v[54:57], v[218:221], v[174:177], v[54:57]
	v_lshl_add_u64 v[174:175], v[108:109], 0, v[98:99]
	v_lshl_add_u64 v[176:177], v[174:175], 0, s[36:37]
	s_mov_b64 s[36:37], 0xe1e8180
	v_mfma_f32_16x16x32_bf16 v[34:37], v[206:209], v[22:25], v[34:37]
	s_add_i32 s23, s23, 1
	v_mfma_f32_16x16x32_bf16 v[74:77], v[210:213], v[22:25], v[74:77]
	v_mfma_f32_16x16x32_bf16 v[70:73], v[214:217], v[22:25], v[70:73]
	v_mfma_f32_16x16x32_bf16 v[78:81], v[218:221], v[22:25], v[78:81]
	ds_read_b128 v[22:25], v6
	ds_read_b128 v[18:21], v7
	v_add_u32_e32 v6, v222, v182
	ds_read_b128 v[10:13], v6
	ds_read_b128 v[6:9], v6 offset:2048
	global_load_lds_dwordx4 v[176:177], off
	v_lshl_add_u64 v[176:177], v[174:175], 0, s[36:37]
	s_add_i32 m0, s34, 0x400
	s_mov_b64 s[36:37], 0xe1f8180
	global_load_lds_dwordx4 v[176:177], off
	v_lshl_add_u64 v[176:177], v[174:175], 0, s[36:37]
	s_add_i32 m0, s34, 0x800
	s_mov_b64 s[36:37], 0xe208180
	global_load_lds_dwordx4 v[176:177], off
	v_lshl_add_u64 v[174:175], v[174:175], 0, s[36:37]
	s_add_i32 m0, s34, 0xc00
	s_mov_b64 s[36:37], 0x4300180
	global_load_lds_dwordx4 v[174:175], off
	v_lshl_add_u64 v[174:175], v[110:111], 0, v[98:99]
	v_lshl_add_u64 v[176:177], v[174:175], 0, s[36:37]
	s_add_i32 m0, s27, 0x8000
	s_mov_b64 s[36:37], 0x4310180
	global_load_lds_dwordx4 v[176:177], off
	v_lshl_add_u64 v[174:175], v[174:175], 0, s[36:37]
	s_add_i32 m0, s27, 0x8400
	v_mfma_f32_16x16x32_bf16 v[50:53], v[206:209], v[178:181], v[50:53]
	global_load_lds_dwordx4 v[174:175], off
	v_mfma_f32_16x16x32_bf16 v[46:49], v[210:213], v[178:181], v[46:49]
	v_mfma_f32_16x16x32_bf16 v[42:45], v[214:217], v[178:181], v[42:45]
	v_mfma_f32_16x16x32_bf16 v[38:41], v[218:221], v[178:181], v[38:41]
	v_mfma_f32_16x16x32_bf16 v[86:89], v[206:209], v[202:205], v[86:89]
	v_mfma_f32_16x16x32_bf16 v[94:97], v[210:213], v[202:205], v[94:97]
	v_mfma_f32_16x16x32_bf16 v[90:93], v[214:217], v[202:205], v[90:93]
	v_mfma_f32_16x16x32_bf16 v[82:85], v[218:221], v[202:205], v[82:85]
	s_add_i32 s13, s13, 1
	s_add_i32 s14, s14, 0xc000
	s_add_i32 s19, s19, 1
	v_lshl_add_u64 v[108:109], v[108:109], 0, s[2:3]
	s_cmp_eq_u32 s14, 0x2dc000
	v_lshl_add_u64 v[110:111], v[110:111], 0, s[2:3]
	s_cbranch_scc0 .LBB0_413
	s_waitcnt lgkmcnt(0)
	v_mfma_f32_16x16x32_bf16 v[34:37], v[22:25], v[30:33], v[34:37]
	v_mfma_f32_16x16x32_bf16 v[74:77], v[18:21], v[30:33], v[74:77]
	v_mfma_f32_16x16x32_bf16 v[70:73], v[10:13], v[30:33], v[70:73]
	v_mfma_f32_16x16x32_bf16 v[30:33], v[6:9], v[30:33], v[78:81]
	v_mfma_f32_16x16x32_bf16 v[66:69], v[22:25], v[26:29], v[66:69]
	v_mfma_f32_16x16x32_bf16 v[62:65], v[18:21], v[26:29], v[62:65]
	v_mfma_f32_16x16x32_bf16 v[58:61], v[10:13], v[26:29], v[58:61]
	v_mfma_f32_16x16x32_bf16 v[26:29], v[6:9], v[26:29], v[54:57]
	v_mfma_f32_16x16x32_bf16 v[50:53], v[22:25], v[14:17], v[50:53]
	v_mfma_f32_16x16x32_bf16 v[46:49], v[18:21], v[14:17], v[46:49]
	v_mfma_f32_16x16x32_bf16 v[42:45], v[10:13], v[14:17], v[42:45]
	v_mfma_f32_16x16x32_bf16 v[14:17], v[6:9], v[14:17], v[38:41]
	v_mfma_f32_16x16x32_bf16 v[22:25], v[22:25], v[2:5], v[86:89]
	s_nop 1
	ds_read_b128 v[38:41], v131
	ds_read_b128 v[54:57], v132 offset:2048
	ds_read_b128 v[78:81], v132 offset:4096
	ds_read_b128 v[86:89], v132 offset:6144
	v_mfma_f32_16x16x32_bf16 v[18:21], v[18:21], v[2:5], v[94:97]
	v_mfma_f32_16x16x32_bf16 v[10:13], v[10:13], v[2:5], v[90:93]
	s_nop 2
	ds_read_b128 v[90:93], v133 offset:32768
	ds_read_b128 v[94:97], v134 offset:34816
	ds_read_b128 v[108:111], v134 offset:36864
	ds_read_b128 v[174:177], v134 offset:38912
	v_mfma_f32_16x16x32_bf16 v[2:5], v[6:9], v[2:5], v[82:85]
	s_waitcnt lgkmcnt(0)
	v_mfma_f32_16x16x32_bf16 v[6:9], v[90:93], v[38:41], v[34:37]
	s_waitcnt vmcnt(6)
	s_waitcnt lgkmcnt(0)
	s_barrier
	v_mfma_f32_16x16x32_bf16 v[34:37], v[94:97], v[38:41], v[74:77]
	v_mfma_f32_16x16x32_bf16 v[70:73], v[108:111], v[38:41], v[70:73]
	v_mfma_f32_16x16x32_bf16 v[30:33], v[174:177], v[38:41], v[30:33]
	v_mfma_f32_16x16x32_bf16 v[38:41], v[90:93], v[54:57], v[66:69]
	v_mfma_f32_16x16x32_bf16 v[62:65], v[94:97], v[54:57], v[62:65]
	v_mfma_f32_16x16x32_bf16 v[58:61], v[108:111], v[54:57], v[58:61]
	v_mfma_f32_16x16x32_bf16 v[26:29], v[174:177], v[54:57], v[26:29]
	v_add_u32_e32 v54, v124, v115
	ds_read_b128 v[54:57], v54
	ds_read_b128 v[66:69], v135 offset:2048
	v_mfma_f32_16x16x32_bf16 v[50:53], v[90:93], v[78:81], v[50:53]
	v_mfma_f32_16x16x32_bf16 v[46:49], v[94:97], v[78:81], v[46:49]
	v_mfma_f32_16x16x32_bf16 v[42:45], v[108:111], v[78:81], v[42:45]
	v_mfma_f32_16x16x32_bf16 v[22:25], v[90:93], v[86:89], v[22:25]
	v_add_u32_e32 v90, 0x20800, v164
	v_mfma_f32_16x16x32_bf16 v[18:21], v[94:97], v[86:89], v[18:21]
	v_add_u32_e32 v94, 0x21000, v164
	v_mfma_f32_16x16x32_bf16 v[10:13], v[108:111], v[86:89], v[10:13]
	v_add_u32_e32 v108, 0x21800, v164
	v_mfma_f32_16x16x32_bf16 v[14:17], v[174:177], v[78:81], v[14:17]
	ds_read_b128 v[74:77], v135 offset:4096
	ds_read_b128 v[78:81], v135 offset:6144
	ds_read_b128 v[82:85], v163
	ds_read_b128 v[90:93], v90
	ds_read_b128 v[94:97], v94
	ds_read_b128 v[108:111], v108
	v_mfma_f32_16x16x32_bf16 v[2:5], v[174:177], v[86:89], v[2:5]
	s_waitcnt lgkmcnt(0)
	v_mfma_f32_16x16x32_bf16 v[6:9], v[82:85], v[54:57], v[6:9]
	v_mfma_f32_16x16x32_bf16 v[34:37], v[90:93], v[54:57], v[34:37]
	v_mfma_f32_16x16x32_bf16 v[70:73], v[94:97], v[54:57], v[70:73]
	v_mfma_f32_16x16x32_bf16 v[30:33], v[108:111], v[54:57], v[30:33]
	v_mfma_f32_16x16x32_bf16 v[54:57], v[90:93], v[66:69], v[62:65]
	s_nop 2
	v_add_u32_e32 v62, v124, v119
	v_mfma_f32_16x16x32_bf16 v[38:41], v[82:85], v[66:69], v[38:41]
	v_mfma_f32_16x16x32_bf16 v[58:61], v[94:97], v[66:69], v[58:61]
	v_mfma_f32_16x16x32_bf16 v[26:29], v[108:111], v[66:69], v[26:29]
	v_mfma_f32_16x16x32_bf16 v[50:53], v[82:85], v[74:77], v[50:53]
	v_mfma_f32_16x16x32_bf16 v[46:49], v[90:93], v[74:77], v[46:49]
	v_mfma_f32_16x16x32_bf16 v[42:45], v[94:97], v[74:77], v[42:45]
	v_mfma_f32_16x16x32_bf16 v[14:17], v[108:111], v[74:77], v[14:17]
	v_mfma_f32_16x16x32_bf16 v[22:25], v[82:85], v[78:81], v[22:25]
	ds_read_b128 v[62:65], v62
	ds_read_b128 v[66:69], v165
	ds_read_b128 v[74:77], v166
	ds_read_b128 v[82:85], v167
	v_mfma_f32_16x16x32_bf16 v[18:21], v[90:93], v[78:81], v[18:21]
	v_mfma_f32_16x16x32_bf16 v[10:13], v[94:97], v[78:81], v[10:13]
	ds_read_b128 v[86:89], v168
	ds_read_b128 v[90:93], v169
	ds_read_b128 v[94:97], v170
	ds_read_b128 v[174:177], v171
	v_mfma_f32_16x16x32_bf16 v[2:5], v[108:111], v[78:81], v[2:5]
	s_waitcnt vmcnt(0)
	s_waitcnt lgkmcnt(0)
	v_mfma_f32_16x16x32_bf16 v[6:9], v[86:89], v[62:65], v[6:9]
	s_waitcnt lgkmcnt(0)
	s_barrier
	v_mfma_f32_16x16x32_bf16 v[34:37], v[90:93], v[62:65], v[34:37]
	v_mfma_f32_16x16x32_bf16 v[70:73], v[94:97], v[62:65], v[70:73]
	v_mfma_f32_16x16x32_bf16 v[30:33], v[174:177], v[62:65], v[30:33]
	v_mfma_f32_16x16x32_bf16 v[38:41], v[86:89], v[66:69], v[38:41]
	v_mfma_f32_16x16x32_bf16 v[54:57], v[90:93], v[66:69], v[54:57]
	v_mfma_f32_16x16x32_bf16 v[58:61], v[94:97], v[66:69], v[58:61]
	v_mfma_f32_16x16x32_bf16 v[26:29], v[174:177], v[66:69], v[26:29]
	v_mfma_f32_16x16x32_bf16 v[50:53], v[86:89], v[74:77], v[50:53]
	v_mfma_f32_16x16x32_bf16 v[46:49], v[90:93], v[74:77], v[46:49]
	v_mfma_f32_16x16x32_bf16 v[42:45], v[94:97], v[74:77], v[42:45]
	v_mfma_f32_16x16x32_bf16 v[14:17], v[174:177], v[74:77], v[14:17]
	ds_read_b128 v[62:65], v164 offset:38912
	ds_read_b128 v[66:69], v164 offset:36864
	ds_read_b128 v[74:77], v164 offset:34816
	ds_read_b128 v[78:81], v161 offset:32768
	v_mfma_f32_16x16x32_bf16 v[22:25], v[86:89], v[82:85], v[22:25]
	v_mfma_f32_16x16x32_bf16 v[18:21], v[90:93], v[82:85], v[18:21]
	v_mfma_f32_16x16x32_bf16 v[10:13], v[94:97], v[82:85], v[10:13]
	ds_read_b128 v[86:89], v173 offset:6144
	ds_read_b128 v[90:93], v173 offset:4096
	ds_read_b128 v[94:97], v173 offset:2048
	ds_read_b128 v[108:111], v172
	v_mfma_f32_16x16x32_bf16 v[2:5], v[174:177], v[82:85], v[2:5]
	s_waitcnt lgkmcnt(0)
	v_mfma_f32_16x16x32_bf16 v[38:41], v[78:81], v[94:97], v[38:41]
	v_add_u32_e32 v82, v114, v119
	v_add_u32_e32 v172, v118, v119
	v_mfma_f32_16x16x32_bf16 v[54:57], v[74:77], v[94:97], v[54:57]
	v_mfma_f32_16x16x32_bf16 v[58:61], v[66:69], v[94:97], v[58:61]
	v_mfma_f32_16x16x32_bf16 v[26:29], v[62:65], v[94:97], v[26:29]
	v_add_u32_e32 v94, v117, v119
	v_mfma_f32_16x16x32_bf16 v[50:53], v[78:81], v[90:93], v[50:53]
	v_mfma_f32_16x16x32_bf16 v[46:49], v[74:77], v[90:93], v[46:49]
	v_mfma_f32_16x16x32_bf16 v[42:45], v[66:69], v[90:93], v[42:45]
	v_mfma_f32_16x16x32_bf16 v[14:17], v[62:65], v[90:93], v[14:17]
	v_add_u32_e32 v90, v116, v119
	v_mfma_f32_16x16x32_bf16 v[6:9], v[78:81], v[108:111], v[6:9]
	v_mfma_f32_16x16x32_bf16 v[34:37], v[74:77], v[108:111], v[34:37]
	v_mfma_f32_16x16x32_bf16 v[70:73], v[66:69], v[108:111], v[70:73]
	v_mfma_f32_16x16x32_bf16 v[30:33], v[62:65], v[108:111], v[30:33]
	v_mfma_f32_16x16x32_bf16 v[78:81], v[78:81], v[86:89], v[22:25]
	s_nop 2
	ds_read_b128 v[22:25], v82
	ds_read_b128 v[82:85], v90 offset:2048
	v_mfma_f32_16x16x32_bf16 v[74:77], v[74:77], v[86:89], v[18:21]
	s_nop 2
	ds_read_b128 v[18:21], v90 offset:4096
	ds_read_b128 v[90:93], v90 offset:6144
	v_mfma_f32_16x16x32_bf16 v[66:69], v[66:69], v[86:89], v[10:13]
	s_nop 2
	ds_read_b128 v[10:13], v94 offset:32768
	ds_read_b128 v[94:97], v172 offset:34816
	ds_read_b128 v[108:111], v172 offset:36864
	ds_read_b128 v[172:175], v172 offset:38912
	v_mfma_f32_16x16x32_bf16 v[2:5], v[62:65], v[86:89], v[2:5]
	s_waitcnt vmcnt(0)
	s_waitcnt lgkmcnt(0)
	v_mfma_f32_16x16x32_bf16 v[2:5], v[172:175], v[90:93], v[2:5]
	s_waitcnt lgkmcnt(0)
	s_barrier
	v_mfma_f32_16x16x32_bf16 v[62:65], v[10:13], v[22:25], v[6:9]
	v_mfma_f32_16x16x32_bf16 v[86:89], v[94:97], v[22:25], v[34:37]
	v_mfma_f32_16x16x32_bf16 v[70:73], v[108:111], v[22:25], v[70:73]
	v_mfma_f32_16x16x32_bf16 v[176:179], v[172:175], v[22:25], v[30:33]
	v_mfma_f32_16x16x32_bf16 v[202:205], v[10:13], v[82:85], v[38:41]
	v_mfma_f32_16x16x32_bf16 v[54:57], v[94:97], v[82:85], v[54:57]
	v_mfma_f32_16x16x32_bf16 v[58:61], v[108:111], v[82:85], v[58:61]
	v_mfma_f32_16x16x32_bf16 v[34:37], v[172:175], v[82:85], v[26:29]
	v_mfma_f32_16x16x32_bf16 v[30:33], v[10:13], v[18:21], v[50:53]
	v_mfma_f32_16x16x32_bf16 v[26:29], v[94:97], v[18:21], v[46:49]
	v_mfma_f32_16x16x32_bf16 v[22:25], v[108:111], v[18:21], v[42:45]
	v_mfma_f32_16x16x32_bf16 v[18:21], v[172:175], v[18:21], v[14:17]
	v_mfma_f32_16x16x32_bf16 v[14:17], v[10:13], v[90:93], v[78:81]
	v_mfma_f32_16x16x32_bf16 v[10:13], v[94:97], v[90:93], v[74:77]
	v_mfma_f32_16x16x32_bf16 v[6:9], v[108:111], v[90:93], v[66:69]
	s_mul_hi_i32 s54, s70, 0x2aaaaaab
	s_lshr_b32 s55, s54, 31
	s_ashr_i32 s54, s54, 2
	s_add_i32 s13, s54, s55
	s_mul_i32 s54, s13, 24
	s_sub_i32 s14, s70, s54
	v_readfirstlane_b32 s54, v137
	s_lshr_b32 s54, s54, 6
	s_and_b32 s19, s54, 1
	s_lshr_b32 s54, s54, 1
	s_lshl_b32 s54, s54, 6
	s_lshl_b32 s50, s14, 8
	s_add_i32 s50, s50, s54
	s_lshl_b32 s51, s13, 7
	s_lshl_b32 s54, s19, 6
	s_add_i32 s51, s51, s54
	s_add_i32 s54, s50, 0xfffff000
	s_ashr_i32 s54, s54, 10
	s_add_i32 s54, s54, 1
	s_cmpk_lt_i32 s50, 0x1000
	s_cselect_b32 s52, 0, s54
	v_readlane_b32 s53, v255, 40
	v_and_b32_e32 v250, 63, v137
	v_and_b32_e32 v251, 15, v250
	v_lshrrev_b32_e32 v252, 4, v250
	s_mul_i32 s54, s53, 3
	s_add_i32 s54, s54, s52
	s_mul_i32 s54, s54, 0x6000
	s_add_u32 s22, s94, 0x6300000
	s_addc_u32 s23, s95, 0
	s_add_u32 s22, s22, s54
	s_addc_u32 s23, s23, 0
	s_add_u32 s26, s94, 0x6348000
	s_addc_u32 s27, s95, 0
	v_add_u32_e32 v242, s50, v251
	v_lshlrev_b32_e32 v242, 12, v242
	s_lshl_b32 s54, s51, 2
	v_lshl_add_u32 v242, v252, 4, v242
	v_add_u32_e32 v242, s54, v242
	s_add_i32 s55, s51, 5120
	s_lshl_b32 s55, s55, 2
	v_lshl_add_u32 v246, v252, 4, s55
	v_readfirstlane_b32 s54, v137
	s_lshr_b32 s54, s54, 6
	s_lshl_b32 s54, s54, 14
	v_and_b32_e32 v242, 3, v251
	v_xor_b32_e32 v242, v242, v252
	v_lshlrev_b32_e32 v242, 4, v242
	v_lshl_add_u32 v242, v251, 8, v242
	v_add_u32_e32 v242, s54, v242
	v_lshl_add_u32 v243, v250, 4, s54
	v_add_u32_e32 v244, s50, v252
	v_lshlrev_b32_e32 v244, 12, v244
	v_xor_b32_e32 v245, v251, v252
	v_lshl_add_u32 v244, v245, 4, v244
	s_lshl_b32 s54, s51, 2
	v_add_u32_e32 v244, s54, v244
	global_load_dwordx4 v[226:229], v246, s[22:23]
	global_load_dwordx4 v[230:233], v246, s[22:23] offset:64
	global_load_dwordx4 v[234:237], v246, s[22:23] offset:128
	global_load_dwordx4 v[238:241], v246, s[22:23] offset:192
	global_load_dwordx4 v[38:41], v244, s[26:27]
	v_add_u32_e32 v245, 0x4000, v244
	global_load_dwordx4 v[42:45], v245, s[26:27]
	v_add_u32_e32 v245, 0x8000, v244
	global_load_dwordx4 v[46:49], v245, s[26:27]
	v_add_u32_e32 v245, 0xc000, v244
	global_load_dwordx4 v[50:53], v245, s[26:27]
	v_add_u32_e32 v245, 0x10000, v244
	global_load_dwordx4 v[66:69], v245, s[26:27]
	v_add_u32_e32 v245, 0x14000, v244
	global_load_dwordx4 v[74:77], v245, s[26:27]
	v_add_u32_e32 v245, 0x18000, v244
	global_load_dwordx4 v[78:81], v245, s[26:27]
	v_add_u32_e32 v245, 0x1c000, v244
	global_load_dwordx4 v[82:85], v245, s[26:27]
	v_add_u32_e32 v245, 0x20000, v244
	global_load_dwordx4 v[90:93], v245, s[26:27]
	v_add_u32_e32 v245, 0x24000, v244
	global_load_dwordx4 v[94:97], v245, s[26:27]
	v_add_u32_e32 v245, 0x28000, v244
	global_load_dwordx4 v[108:111], v245, s[26:27]
	v_add_u32_e32 v245, 0x2c000, v244
	global_load_dwordx4 v[172:175], v245, s[26:27]
	v_add_u32_e32 v245, 0x30000, v244
	global_load_dwordx4 v[206:209], v245, s[26:27]
	v_add_u32_e32 v245, 0x34000, v244
	global_load_dwordx4 v[210:213], v245, s[26:27]
	v_add_u32_e32 v245, 0x38000, v244
	global_load_dwordx4 v[214:217], v245, s[26:27]
	v_add_u32_e32 v245, 0x3c000, v244
	global_load_dwordx4 v[218:221], v245, s[26:27]
	s_waitcnt vmcnt(15)
	ds_write_b128 v243, v[38:41] offset:0
	s_waitcnt vmcnt(14)
	ds_write_b128 v243, v[42:45] offset:1024
	s_waitcnt vmcnt(13)
	ds_write_b128 v243, v[46:49] offset:2048
	s_waitcnt vmcnt(12)
	ds_write_b128 v243, v[50:53] offset:3072
	s_waitcnt vmcnt(11)
	ds_write_b128 v243, v[66:69] offset:4096
	s_waitcnt vmcnt(10)
	ds_write_b128 v243, v[74:77] offset:5120
	s_waitcnt vmcnt(9)
	ds_write_b128 v243, v[78:81] offset:6144
	s_waitcnt vmcnt(8)
	ds_write_b128 v243, v[82:85] offset:7168
	s_waitcnt vmcnt(7)
	ds_write_b128 v243, v[90:93] offset:8192
	s_waitcnt vmcnt(6)
	ds_write_b128 v243, v[94:97] offset:9216
	s_waitcnt vmcnt(5)
	ds_write_b128 v243, v[108:111] offset:10240
	s_waitcnt vmcnt(4)
	ds_write_b128 v243, v[172:175] offset:11264
	s_waitcnt vmcnt(3)
	ds_write_b128 v243, v[206:209] offset:12288
	s_waitcnt vmcnt(2)
	ds_write_b128 v243, v[210:213] offset:13312
	s_waitcnt vmcnt(1)
	ds_write_b128 v243, v[214:217] offset:14336
	s_waitcnt vmcnt(0)
	ds_write_b128 v243, v[218:221] offset:15360
	s_waitcnt lgkmcnt(0)
	ds_read_b128 v[38:41], v242 offset:0
	ds_read_b128 v[42:45], v242 offset:64
	ds_read_b128 v[46:49], v242 offset:128
	ds_read_b128 v[50:53], v242 offset:192
	ds_read_b128 v[66:69], v242 offset:4096
	ds_read_b128 v[74:77], v242 offset:4160
	ds_read_b128 v[78:81], v242 offset:4224
	ds_read_b128 v[82:85], v242 offset:4288
	ds_read_b128 v[90:93], v242 offset:8192
	ds_read_b128 v[94:97], v242 offset:8256
	ds_read_b128 v[108:111], v242 offset:8320
	ds_read_b128 v[172:175], v242 offset:8384
	ds_read_b128 v[206:209], v242 offset:12288
	ds_read_b128 v[210:213], v242 offset:12352
	ds_read_b128 v[214:217], v242 offset:12416
	ds_read_b128 v[218:221], v242 offset:12480
	v_mov_b32_e32 v248, 0x3fd744fd
	v_mov_b32_e32 v249, 0x3fd744fd
	s_waitcnt lgkmcnt(12)
	v_pk_mul_f32 v[38:39], v[38:39], v[248:249]
	v_pk_mul_f32 v[40:41], v[40:41], v[248:249]
	v_pk_fma_f32 v[62:63], v[62:63], v[226:227], v[38:39]
	v_pk_fma_f32 v[64:65], v[64:65], v[228:229], v[40:41]
	v_pk_mul_f32 v[42:43], v[42:43], v[248:249]
	v_pk_mul_f32 v[44:45], v[44:45], v[248:249]
	v_pk_fma_f32 v[86:87], v[86:87], v[230:231], v[42:43]
	v_pk_fma_f32 v[88:89], v[88:89], v[232:233], v[44:45]
	v_pk_mul_f32 v[46:47], v[46:47], v[248:249]
	v_pk_mul_f32 v[48:49], v[48:49], v[248:249]
	v_pk_fma_f32 v[70:71], v[70:71], v[234:235], v[46:47]
	v_pk_fma_f32 v[72:73], v[72:73], v[236:237], v[48:49]
	v_pk_mul_f32 v[50:51], v[50:51], v[248:249]
	v_pk_mul_f32 v[52:53], v[52:53], v[248:249]
	v_pk_fma_f32 v[176:177], v[176:177], v[238:239], v[50:51]
	v_pk_fma_f32 v[178:179], v[178:179], v[240:241], v[52:53]
	s_waitcnt lgkmcnt(8)
	v_pk_mul_f32 v[66:67], v[66:67], v[248:249]
	v_pk_mul_f32 v[68:69], v[68:69], v[248:249]
	v_pk_fma_f32 v[202:203], v[202:203], v[226:227], v[66:67]
	v_pk_fma_f32 v[204:205], v[204:205], v[228:229], v[68:69]
	v_pk_mul_f32 v[74:75], v[74:75], v[248:249]
	v_pk_mul_f32 v[76:77], v[76:77], v[248:249]
	v_pk_fma_f32 v[54:55], v[54:55], v[230:231], v[74:75]
	v_pk_fma_f32 v[56:57], v[56:57], v[232:233], v[76:77]
	v_pk_mul_f32 v[78:79], v[78:79], v[248:249]
	v_pk_mul_f32 v[80:81], v[80:81], v[248:249]
	v_pk_fma_f32 v[58:59], v[58:59], v[234:235], v[78:79]
	v_pk_fma_f32 v[60:61], v[60:61], v[236:237], v[80:81]
	v_pk_mul_f32 v[82:83], v[82:83], v[248:249]
	v_pk_mul_f32 v[84:85], v[84:85], v[248:249]
	v_pk_fma_f32 v[34:35], v[34:35], v[238:239], v[82:83]
	v_pk_fma_f32 v[36:37], v[36:37], v[240:241], v[84:85]
	s_waitcnt lgkmcnt(4)
	v_pk_mul_f32 v[90:91], v[90:91], v[248:249]
	v_pk_mul_f32 v[92:93], v[92:93], v[248:249]
	v_pk_fma_f32 v[30:31], v[30:31], v[226:227], v[90:91]
	v_pk_fma_f32 v[32:33], v[32:33], v[228:229], v[92:93]
	v_pk_mul_f32 v[94:95], v[94:95], v[248:249]
	v_pk_mul_f32 v[96:97], v[96:97], v[248:249]
	v_pk_fma_f32 v[26:27], v[26:27], v[230:231], v[94:95]
	v_pk_fma_f32 v[28:29], v[28:29], v[232:233], v[96:97]
	v_pk_mul_f32 v[108:109], v[108:109], v[248:249]
	v_pk_mul_f32 v[110:111], v[110:111], v[248:249]
	v_pk_fma_f32 v[22:23], v[22:23], v[234:235], v[108:109]
	v_pk_fma_f32 v[24:25], v[24:25], v[236:237], v[110:111]
	v_pk_mul_f32 v[172:173], v[172:173], v[248:249]
	v_pk_mul_f32 v[174:175], v[174:175], v[248:249]
	v_pk_fma_f32 v[18:19], v[18:19], v[238:239], v[172:173]
	v_pk_fma_f32 v[20:21], v[20:21], v[240:241], v[174:175]
	s_waitcnt lgkmcnt(0)
	v_pk_mul_f32 v[206:207], v[206:207], v[248:249]
	v_pk_mul_f32 v[208:209], v[208:209], v[248:249]
	v_pk_fma_f32 v[14:15], v[14:15], v[226:227], v[206:207]
	v_pk_fma_f32 v[16:17], v[16:17], v[228:229], v[208:209]
	v_pk_mul_f32 v[210:211], v[210:211], v[248:249]
	v_pk_mul_f32 v[212:213], v[212:213], v[248:249]
	v_pk_fma_f32 v[10:11], v[10:11], v[230:231], v[210:211]
	v_pk_fma_f32 v[12:13], v[12:13], v[232:233], v[212:213]
	v_pk_mul_f32 v[214:215], v[214:215], v[248:249]
	v_pk_mul_f32 v[216:217], v[216:217], v[248:249]
	v_pk_fma_f32 v[6:7], v[6:7], v[234:235], v[214:215]
	v_pk_fma_f32 v[8:9], v[8:9], v[236:237], v[216:217]
	v_pk_mul_f32 v[218:219], v[218:219], v[248:249]
	v_pk_mul_f32 v[220:221], v[220:221], v[248:249]
	v_pk_fma_f32 v[2:3], v[2:3], v[238:239], v[218:219]
	v_pk_fma_f32 v[4:5], v[4:5], v[240:241], v[220:221]
	v_pk_mul_f32 v[208:209], v[62:63], v[62:63]
	v_pk_add_f32 v[206:207], v[62:63], v[64:65]
	v_pk_fma_f32 v[208:209], v[64:65], v[64:65], v[208:209]
	v_pk_add_f32 v[206:207], v[206:207], v[86:87]
	v_pk_fma_f32 v[208:209], v[86:87], v[86:87], v[208:209]
	v_pk_add_f32 v[206:207], v[206:207], v[88:89]
	v_pk_fma_f32 v[208:209], v[88:89], v[88:89], v[208:209]
	v_pk_add_f32 v[206:207], v[206:207], v[70:71]
	v_pk_fma_f32 v[208:209], v[70:71], v[70:71], v[208:209]
	v_pk_add_f32 v[206:207], v[206:207], v[72:73]
	v_pk_fma_f32 v[208:209], v[72:73], v[72:73], v[208:209]
	v_pk_add_f32 v[206:207], v[206:207], v[176:177]
	v_pk_fma_f32 v[208:209], v[176:177], v[176:177], v[208:209]
	v_pk_add_f32 v[206:207], v[206:207], v[178:179]
	v_pk_fma_f32 v[208:209], v[178:179], v[178:179], v[208:209]
	v_add_f32_e32 v206, v206, v207
	v_add_f32_e32 v208, v208, v209
	v_pk_mul_f32 v[212:213], v[202:203], v[202:203]
	v_pk_add_f32 v[210:211], v[202:203], v[204:205]
	v_pk_fma_f32 v[212:213], v[204:205], v[204:205], v[212:213]
	v_pk_add_f32 v[210:211], v[210:211], v[54:55]
	v_pk_fma_f32 v[212:213], v[54:55], v[54:55], v[212:213]
	v_pk_add_f32 v[210:211], v[210:211], v[56:57]
	v_pk_fma_f32 v[212:213], v[56:57], v[56:57], v[212:213]
	v_pk_add_f32 v[210:211], v[210:211], v[58:59]
	v_pk_fma_f32 v[212:213], v[58:59], v[58:59], v[212:213]
	v_pk_add_f32 v[210:211], v[210:211], v[60:61]
	v_pk_fma_f32 v[212:213], v[60:61], v[60:61], v[212:213]
	v_pk_add_f32 v[210:211], v[210:211], v[34:35]
	v_pk_fma_f32 v[212:213], v[34:35], v[34:35], v[212:213]
	v_pk_add_f32 v[210:211], v[210:211], v[36:37]
	v_pk_fma_f32 v[212:213], v[36:37], v[36:37], v[212:213]
	v_add_f32_e32 v210, v210, v211
	v_add_f32_e32 v212, v212, v213
	v_pk_mul_f32 v[216:217], v[30:31], v[30:31]
	v_pk_add_f32 v[214:215], v[30:31], v[32:33]
	v_pk_fma_f32 v[216:217], v[32:33], v[32:33], v[216:217]
	v_pk_add_f32 v[214:215], v[214:215], v[26:27]
	v_pk_fma_f32 v[216:217], v[26:27], v[26:27], v[216:217]
	v_pk_add_f32 v[214:215], v[214:215], v[28:29]
	v_pk_fma_f32 v[216:217], v[28:29], v[28:29], v[216:217]
	v_pk_add_f32 v[214:215], v[214:215], v[22:23]
	v_pk_fma_f32 v[216:217], v[22:23], v[22:23], v[216:217]
	v_pk_add_f32 v[214:215], v[214:215], v[24:25]
	v_pk_fma_f32 v[216:217], v[24:25], v[24:25], v[216:217]
	v_pk_add_f32 v[214:215], v[214:215], v[18:19]
	v_pk_fma_f32 v[216:217], v[18:19], v[18:19], v[216:217]
	v_pk_add_f32 v[214:215], v[214:215], v[20:21]
	v_pk_fma_f32 v[216:217], v[20:21], v[20:21], v[216:217]
	v_add_f32_e32 v214, v214, v215
	v_add_f32_e32 v216, v216, v217
	v_pk_mul_f32 v[220:221], v[14:15], v[14:15]
	v_pk_add_f32 v[218:219], v[14:15], v[16:17]
	v_pk_fma_f32 v[220:221], v[16:17], v[16:17], v[220:221]
	v_pk_add_f32 v[218:219], v[218:219], v[10:11]
	v_pk_fma_f32 v[220:221], v[10:11], v[10:11], v[220:221]
	v_pk_add_f32 v[218:219], v[218:219], v[12:13]
	v_pk_fma_f32 v[220:221], v[12:13], v[12:13], v[220:221]
	v_pk_add_f32 v[218:219], v[218:219], v[6:7]
	v_pk_fma_f32 v[220:221], v[6:7], v[6:7], v[220:221]
	v_pk_add_f32 v[218:219], v[218:219], v[8:9]
	v_pk_fma_f32 v[220:221], v[8:9], v[8:9], v[220:221]
	v_pk_add_f32 v[218:219], v[218:219], v[2:3]
	v_pk_fma_f32 v[220:221], v[2:3], v[2:3], v[220:221]
	v_pk_add_f32 v[218:219], v[218:219], v[4:5]
	v_pk_fma_f32 v[220:221], v[4:5], v[4:5], v[220:221]
	v_add_f32_e32 v218, v218, v219
	v_add_f32_e32 v220, v220, v221
	s_nop 1
	v_permlane16_swap_b32_e32 v206, v210
	v_permlane16_swap_b32_e32 v214, v218
	v_permlane16_swap_b32_e32 v208, v212
	v_permlane16_swap_b32_e32 v216, v220
	v_add_f32_e32 v206, v206, v210
	v_add_f32_e32 v214, v214, v218
	v_add_f32_e32 v208, v208, v212
	v_add_f32_e32 v216, v216, v220
	s_nop 1
	v_permlane32_swap_b32_e32 v206, v214
	v_permlane32_swap_b32_e32 v208, v216
	v_add_f32_e32 v248, v206, v214
	v_add_f32_e32 v249, v208, v216
	s_lshl_b32 s54, s53, 1
	s_add_i32 s54, s54, 0x2c7e91a1
	v_mov_b32_e32 v218, v248
	v_mov_b32_e32 v219, s54
	v_mov_b32_e32 v220, v249
	v_mov_b32_e32 v221, s54
	v_mov_b32_e32 v249, s54
	s_add_u32 s34, s94, 0xc9d8000
	s_addc_u32 s35, s95, 0
	v_add_u32_e32 v247, s50, v250
	v_lshlrev_b32_e32 v247, 4, v247
	s_lshl_b32 s55, s13, 1
	s_add_i32 s55, s55, s19
	s_mul_i32 s55, s55, 0x18000
	v_add_u32_e32 v246, s55, v247
	global_store_dwordx4 v246, v[218:221], s[34:35] sc1
	v_readlane_b32 s36, v253, 15
	v_readlane_b32 s37, v253, 16
	v_readlane_b32 s48, v253, 17
	v_readlane_b32 s49, v253, 18
	s_lshl_b32 s54, s53, 10
	s_add_i32 s54, s54, s51
	s_lshl_b32 s54, s54, 2
	v_lshl_add_u32 v222, v252, 4, s54
	s_nop 3
	global_load_dwordx4 v[66:69], v222, s[36:37]
	global_load_dwordx4 v[74:77], v222, s[36:37] offset:64
	global_load_dwordx4 v[78:81], v222, s[36:37] offset:128
	global_load_dwordx4 v[82:85], v222, s[36:37] offset:192
	global_load_dwordx4 v[90:93], v222, s[48:49]
	global_load_dwordx4 v[94:97], v222, s[48:49] offset:64
	global_load_dwordx4 v[108:111], v222, s[48:49] offset:128
	global_load_dwordx4 v[172:175], v222, s[48:49] offset:192
	s_add_u32 s22, s22, 0x12000
	s_addc_u32 s23, s23, 0
	s_add_i32 s54, s51, 0
	s_lshl_b32 s54, s54, 2
	v_lshl_add_u32 v222, v252, 4, s54
	v_add_u32_e32 v246, 0x1000, v222
	s_cmp_eq_u32 s53, 3
	s_cbranch_scc1 .Lln2_nosh
	global_load_dwordx4 v[38:41], v222, s[22:23]
	global_load_dwordx4 v[42:45], v222, s[22:23] offset:64
	global_load_dwordx4 v[46:49], v222, s[22:23] offset:128
	global_load_dwordx4 v[50:53], v222, s[22:23] offset:192
